# phase-14 top-16 radix select: bit loop exits as soon as the remaining candidates are exactly the number still to select
# speedup vs baseline: 1.0109x; 1.0089x over previous
; __device__ __forceinline__ void phase_nsa_cmp(const Params& p, u16* sm) {
;     ...
;     for (int qi = 0; qi < 4; ++qi) {
;       const int q = wave * 4 + qi, tq = t0 + q, cur = tq >> 6, n = lane;
;       const bool causal = (n <= cur);
;       const bool forced = (n == 0) || (n == cur) || (n == cur - 1);
;       const float sc = causal ? (Imp[q * 64 + n] + (forced ? 1e4f : 0.f)) : -1e30f;
;       int rank = 0;
;       Imp[q * 64 + n] = sc;
;       __builtin_amdgcn_wave_barrier();
; #pragma unroll 8
;       for (int n2 = 0; n2 < 64; ++n2) {
;         const float s2 = Imp[q * 64 + n2];
;         rank += ((s2 > sc) || (s2 == sc && n2 < n)) ? 1 : 0;
;       }
;       const unsigned long long mk = __ballot(causal && rank < 16);
;       if (lane == 0) p.msk[(size_t)(b * 2 + g) * SEQ + tq] = mk;
.Lrs0_bit:
	v_and_b32_e32 v3, s27, v2
	v_cmp_ne_u32_e64 s[22:23], 0, v3
	s_and_b64 s[22:23], s[22:23], s[18:19]
	s_bcnt1_i32_b64 s26, s[22:23]
	s_andn2_b64 s[24:25], s[18:19], s[22:23]
	s_or_b64 s[14:15], s[16:17], s[22:23]
	s_cmp_ge_u32 s26, s20
	s_cselect_b64 s[18:19], s[22:23], s[24:25]
	s_cselect_b64 s[16:17], s[16:17], s[14:15]
	s_cselect_b32 s26, 0, s26
	s_bcnt1_i32_b64 s21, s[18:19]
	s_sub_u32 s20, s20, s26
	s_cmp_eq_u32 s21, s20
	s_cbranch_scc1 .Lrs0_all
	s_lshr_b32 s27, s27, 1
	s_cbranch_scc1 .Lrs0_bit
.Lrs0_tie:
	s_ff1_i32_b64 s21, s[18:19]
	s_bitset1_b64 s[16:17], s21
	s_bitset0_b64 s[18:19], s21
	s_sub_u32 s20, s20, 1
	s_cmp_lg_u32 s20, 0
	s_cbranch_scc1 .Lrs0_tie
	s_branch .Lrs0_done
.Lrs0_all:
	s_or_b64 s[16:17], s[16:17], s[18:19]
